# v98 + grid-barrier poll loops back off (s_sleep 1 -> 3)
# baseline (speedup 1.0000x reference)
; __device__ __forceinline__ unsigned xb_ld(unsigned* p)              { return __hip_atomic_load(p, __ATOMIC_RELAXED, __HIP_MEMORY_SCOPE_AGENT); }
; __device__ __forceinline__ unsigned xb_add(unsigned* p, unsigned v) { return __hip_atomic_fetch_add(p, v, __ATOMIC_RELAXED, __HIP_MEMORY_SCOPE_AGENT); }
; #define XB_SPIN(cond, bar) do { unsigned _sp = 0; while (cond) { __builtin_amdgcn_s_sleep(1); \
;     if ((++_sp & 255u) == 0u) { if (xb_ld(&(bar)[XB_TMO])) break; if (_sp > XB_SPIN_CAP) { atomicAdd(&(bar)[XB_TMO], 1u); break; } } } } while (0)
; __device__ __forceinline__ void xcd_barrier(const XcdBarrier& b, int tid) {
;     ...
;             else XB_SPIN(xb_ld(&bar[XB_TOPGEN]) == tg, bar);
;             __builtin_amdgcn_fence(__ATOMIC_ACQUIRE, "agent");
;             xb_add(&bar[XB_XGEN(b.x)], 1u);
;             asm volatile("s_waitcnt vmcnt(0)" ::: "memory");
;         } else {
;             XB_SPIN(xb_ld(&bar[XB_XGEN(b.x)]) == gen, bar);
.LBB0_98:
	s_sleep 3
	global_load_dword v3, v1, s[6:7] offset:32 sc1
	s_waitcnt vmcnt(0)
	v_and_b32_e32 v3, 0xffff0000, v3
	v_cmp_ne_u32_e32 vcc, v3, v2
	s_or_b64 s[8:9], vcc, s[8:9]
	s_andn2_b64 exec, exec, s[8:9]
	s_cbranch_execnz .LBB0_98

; __device__ __forceinline__ unsigned xb_ld(unsigned* p)              { return __hip_atomic_load(p, __ATOMIC_RELAXED, __HIP_MEMORY_SCOPE_AGENT); }
; __device__ __forceinline__ void xcd_barrier_complete(unsigned* bar, unsigned x, unsigned& nloc, unsigned& nx) {
;     const unsigned G = gridDim.x * gridDim.y * gridDim.z;
;     unsigned sum, cnt, mine, sp = 0u;
;     for (;;) {
;         sum = 0u; cnt = 0u; mine = 0u;
; #pragma unroll
;         for (unsigned j = 0; j < 16; ++j) { const unsigned c = xb_ld(&bar[XB_XCNT(j)]); sum += c; cnt += (c > 0u) ? 1u : 0u; mine = (j == x) ? c : mine; }
;         if (sum == G) break;
;         __builtin_amdgcn_s_sleep(1);
;         if ((++sp & 255u) == 0u) { if (xb_ld(&bar[XB_TMO])) break; if (sp > XB_SPIN_CAP) { atomicAdd(&bar[XB_TMO], 1u); break; } }
;     }
;     nloc = mine > 0u ? mine : 1u; nx = cnt > 0u ? cnt : 1u;
; }
.LBB0_105:
	global_load_dword v16, v17, s[8:9] sc1
	s_waitcnt lgkmcnt(0)
	global_load_dword v1, v17, s[10:11] sc1
	global_load_dword v2, v17, s[12:13] sc1
	global_load_dword v3, v17, s[14:15] sc1
	global_load_dword v4, v17, s[18:19] sc1
	global_load_dword v5, v17, s[20:21] sc1
	global_load_dword v6, v17, s[22:23] sc1
	global_load_dword v7, v17, s[24:25] sc1
	global_load_dword v8, v17, s[26:27] sc1
	global_load_dword v9, v17, s[28:29] sc1
	global_load_dword v10, v17, s[30:31] sc1
	global_load_dword v11, v17, s[34:35] sc1
	global_load_dword v12, v17, s[36:37] sc1
	global_load_dword v13, v17, s[38:39] sc1
	global_load_dword v14, v17, s[40:41] sc1
	global_load_dword v15, v17, s[42:43] sc1
	s_mov_b64 s[44:45], -1
	s_mov_b64 s[46:47], -1
	s_waitcnt vmcnt(14)
	v_add_u32_e32 v18, v1, v16
	s_waitcnt vmcnt(13)
	v_add_u32_e32 v18, v18, v2
	s_waitcnt vmcnt(12)
	v_add_u32_e32 v18, v18, v3
	s_waitcnt vmcnt(11)
	v_add_u32_e32 v18, v18, v4
	s_waitcnt vmcnt(10)
	v_add_u32_e32 v18, v18, v5
	s_waitcnt vmcnt(9)
	v_add_u32_e32 v18, v18, v6
	s_waitcnt vmcnt(8)
	v_add_u32_e32 v18, v18, v7
	s_waitcnt vmcnt(7)
	v_add_u32_e32 v18, v18, v8
	s_waitcnt vmcnt(6)
	v_add_u32_e32 v18, v18, v9
	s_waitcnt vmcnt(5)
	v_add_u32_e32 v18, v18, v10
	s_waitcnt vmcnt(4)
	v_add_u32_e32 v18, v18, v11
	s_waitcnt vmcnt(3)
	v_add_u32_e32 v18, v18, v12
	s_waitcnt vmcnt(2)
	v_add_u32_e32 v18, v18, v13
	s_waitcnt vmcnt(1)
	v_add_u32_e32 v18, v18, v14
	s_waitcnt vmcnt(0)
	v_add_u32_e32 v18, v18, v15
	v_cmp_eq_u32_e32 vcc, s33, v18
	s_cbranch_vccnz .LBB0_104
	s_and_b32 s44, s50, 0xff
	s_cmp_eq_u32 s44, 0
	s_mov_b64 s[44:45], -1
	s_mov_b64 s[48:49], -1
	s_sleep 3
	s_cbranch_scc1 .LBB0_109
	s_and_b64 vcc, exec, s[48:49]
	s_cbranch_vccz .LBB0_104

.LBB0_123:
	s_and_b32 s24, s28, 0xff
	s_mov_b64 s[22:23], -1
	s_cmp_lg_u32 s24, 0
	s_mov_b64 s[26:27], -1
	s_sleep 3
	s_cbranch_scc0 .LBB0_126
	s_and_b64 vcc, exec, s[26:27]
	s_cbranch_vccz .LBB0_122

.LBB0_140:
	s_and_b32 s22, s28, 0xff
	s_cmp_lg_u32 s22, 0
	s_mov_b64 s[24:25], -1
	s_sleep 3
	s_cbranch_scc0 .LBB0_143
	s_mov_b64 s[26:27], -1
	s_and_b64 vcc, exec, s[24:25]
	s_cbranch_vccz .LBB0_139

; __device__ __forceinline__ unsigned xb_ld(unsigned* p)              { return __hip_atomic_load(p, __ATOMIC_RELAXED, __HIP_MEMORY_SCOPE_AGENT); }
; __device__ __forceinline__ unsigned xb_add(unsigned* p, unsigned v) { return __hip_atomic_fetch_add(p, v, __ATOMIC_RELAXED, __HIP_MEMORY_SCOPE_AGENT); }
; #define XB_SPIN(cond, bar) do { unsigned _sp = 0; while (cond) { __builtin_amdgcn_s_sleep(1); \
;     if ((++_sp & 255u) == 0u) { if (xb_ld(&(bar)[XB_TMO])) break; if (_sp > XB_SPIN_CAP) { atomicAdd(&(bar)[XB_TMO], 1u); break; } } } } while (0)
; __device__ __forceinline__ void xcd_barrier(const XcdBarrier& b, int tid) {
;     ...
;             else XB_SPIN(xb_ld(&bar[XB_TOPGEN]) == tg, bar);
;             __builtin_amdgcn_fence(__ATOMIC_ACQUIRE, "agent");
;             xb_add(&bar[XB_XGEN(b.x)], 1u);
;             asm volatile("s_waitcnt vmcnt(0)" ::: "memory");
;         } else {
;             XB_SPIN(xb_ld(&bar[XB_XGEN(b.x)]) == gen, bar);
.LBB0_239:
	s_sleep 3
	global_load_dword v1, v213, s[2:3] offset:32 sc1
	s_waitcnt vmcnt(0)
	v_and_b32_e32 v1, 0xffff0000, v1
	v_cmp_ne_u32_e32 vcc, v1, v0
	s_or_b64 s[6:7], vcc, s[6:7]
	s_andn2_b64 exec, exec, s[6:7]
	s_cbranch_execnz .LBB0_239

; __device__ __forceinline__ unsigned xb_ld(unsigned* p)              { return __hip_atomic_load(p, __ATOMIC_RELAXED, __HIP_MEMORY_SCOPE_AGENT); }
; __device__ __forceinline__ void xcd_barrier_complete(unsigned* bar, unsigned x, unsigned& nloc, unsigned& nx) {
;     const unsigned G = gridDim.x * gridDim.y * gridDim.z;
;     unsigned sum, cnt, mine, sp = 0u;
;     for (;;) {
;         sum = 0u; cnt = 0u; mine = 0u;
; #pragma unroll
;         for (unsigned j = 0; j < 16; ++j) { const unsigned c = xb_ld(&bar[XB_XCNT(j)]); sum += c; cnt += (c > 0u) ? 1u : 0u; mine = (j == x) ? c : mine; }
;         if (sum == G) break;
;         __builtin_amdgcn_s_sleep(1);
;         if ((++sp & 255u) == 0u) { if (xb_ld(&bar[XB_TMO])) break; if (sp > XB_SPIN_CAP) { atomicAdd(&bar[XB_TMO], 1u); break; } }
;     }
;     nloc = mine > 0u ? mine : 1u; nx = cnt > 0u ? cnt : 1u;
; }
.LBB0_246:
	v_readlane_b32 s2, v254, 5
	v_readlane_b32 s3, v254, 6
	global_load_dword v2, v213, s[90:91] sc1
	s_waitcnt lgkmcnt(0)
	global_load_dword v0, v213, s[92:93] sc1
	global_load_dword v1, v213, s[86:87] sc1
	s_mov_b64 s[6:7], -1
	s_waitcnt vmcnt(1)
	v_add_u32_e32 v16, v0, v2
	global_load_dword v3, v213, s[2:3] sc1
	v_readlane_b32 s2, v254, 7
	v_readlane_b32 s3, v254, 8
	s_waitcnt vmcnt(1)
	v_add_u32_e32 v16, v16, v1
	s_waitcnt vmcnt(0)
	v_add_u32_e32 v16, v16, v3
	s_nop 0
	global_load_dword v4, v213, s[2:3] sc1
	v_readlane_b32 s2, v254, 9
	v_readlane_b32 s3, v254, 10
	s_waitcnt vmcnt(0)
	v_add_u32_e32 v16, v16, v4
	s_nop 2
	global_load_dword v5, v213, s[2:3] sc1
	v_readlane_b32 s2, v254, 11
	v_readlane_b32 s3, v254, 12
	s_waitcnt vmcnt(0)
	v_add_u32_e32 v16, v16, v5
	s_nop 2
	global_load_dword v6, v213, s[2:3] sc1
	v_readlane_b32 s2, v254, 13
	v_readlane_b32 s3, v254, 14
	s_waitcnt vmcnt(0)
	v_add_u32_e32 v16, v16, v6
	s_nop 2
	global_load_dword v7, v213, s[2:3] sc1
	v_readlane_b32 s2, v254, 15
	v_readlane_b32 s3, v254, 16
	s_waitcnt vmcnt(0)
	v_add_u32_e32 v16, v16, v7
	s_nop 2
	global_load_dword v8, v213, s[2:3] sc1
	v_readlane_b32 s2, v254, 17
	v_readlane_b32 s3, v254, 18
	s_waitcnt vmcnt(0)
	v_add_u32_e32 v16, v16, v8
	s_nop 2
	global_load_dword v9, v213, s[2:3] sc1
	v_readlane_b32 s2, v254, 19
	v_readlane_b32 s3, v254, 20
	s_waitcnt vmcnt(0)
	v_add_u32_e32 v16, v16, v9
	s_nop 2
	global_load_dword v10, v213, s[2:3] sc1
	v_readlane_b32 s2, v254, 21
	v_readlane_b32 s3, v254, 22
	s_waitcnt vmcnt(0)
	v_add_u32_e32 v16, v16, v10
	s_nop 2
	global_load_dword v11, v213, s[2:3] sc1
	v_readlane_b32 s2, v254, 23
	v_readlane_b32 s3, v254, 24
	s_waitcnt vmcnt(0)
	v_add_u32_e32 v16, v16, v11
	s_nop 2
	global_load_dword v12, v213, s[2:3] sc1
	v_readlane_b32 s2, v254, 25
	v_readlane_b32 s3, v254, 26
	s_waitcnt vmcnt(0)
	v_add_u32_e32 v16, v16, v12
	s_nop 2
	global_load_dword v13, v213, s[2:3] sc1
	v_readlane_b32 s2, v254, 27
	v_readlane_b32 s3, v254, 28
	s_waitcnt vmcnt(0)
	v_add_u32_e32 v16, v16, v13
	s_nop 2
	global_load_dword v14, v213, s[2:3] sc1
	v_readlane_b32 s2, v254, 29
	v_readlane_b32 s3, v254, 30
	s_waitcnt vmcnt(0)
	v_add_u32_e32 v16, v16, v14
	s_nop 2
	global_load_dword v15, v213, s[2:3] sc1
	s_mov_b64 s[2:3], -1
	s_waitcnt vmcnt(0)
	v_add_u32_e32 v16, v16, v15
	v_cmp_eq_u32_e32 vcc, s83, v16
	s_cbranch_vccnz .LBB0_245
	s_and_b32 s2, s4, 0xff
	s_cmp_eq_u32 s2, 0
	s_mov_b64 s[2:3], -1
	s_mov_b64 s[12:13], -1
	s_sleep 3
	s_cbranch_scc1 .LBB0_250
	s_and_b64 vcc, exec, s[12:13]
	s_cbranch_vccz .LBB0_245

; __device__ __forceinline__ unsigned xb_ld(unsigned* p)              { return __hip_atomic_load(p, __ATOMIC_RELAXED, __HIP_MEMORY_SCOPE_AGENT); }
; __device__ __forceinline__ void xcd_barrier_complete(unsigned* bar, unsigned x, unsigned& nloc, unsigned& nx) {
;     const unsigned G = gridDim.x * gridDim.y * gridDim.z;
;     unsigned sum, cnt, mine, sp = 0u;
;     for (;;) {
;         sum = 0u; cnt = 0u; mine = 0u;
; #pragma unroll
;         for (unsigned j = 0; j < 16; ++j) { const unsigned c = xb_ld(&bar[XB_XCNT(j)]); sum += c; cnt += (c > 0u) ? 1u : 0u; mine = (j == x) ? c : mine; }
;         if (sum == G) break;
;         __builtin_amdgcn_s_sleep(1);
;         if ((++sp & 255u) == 0u) { if (xb_ld(&bar[XB_TMO])) break; if (sp > XB_SPIN_CAP) { atomicAdd(&bar[XB_TMO], 1u); break; } }
;     }
;     nloc = mine > 0u ? mine : 1u; nx = cnt > 0u ? cnt : 1u;
; }
.LBB0_271:
	v_readlane_b32 s2, v254, 5
	v_readlane_b32 s3, v254, 6
	global_load_dword v2, v213, s[90:91] sc1
	s_waitcnt lgkmcnt(0)
	global_load_dword v0, v213, s[92:93] sc1
	global_load_dword v1, v213, s[86:87] sc1
	s_mov_b64 s[6:7], -1
	s_waitcnt vmcnt(1)
	v_add_u32_e32 v16, v0, v2
	global_load_dword v3, v213, s[2:3] sc1
	v_readlane_b32 s2, v254, 7
	v_readlane_b32 s3, v254, 8
	s_waitcnt vmcnt(1)
	v_add_u32_e32 v16, v16, v1
	s_waitcnt vmcnt(0)
	v_add_u32_e32 v16, v16, v3
	s_nop 0
	global_load_dword v4, v213, s[2:3] sc1
	v_readlane_b32 s2, v254, 9
	v_readlane_b32 s3, v254, 10
	s_waitcnt vmcnt(0)
	v_add_u32_e32 v16, v16, v4
	s_nop 2
	global_load_dword v5, v213, s[2:3] sc1
	v_readlane_b32 s2, v254, 11
	v_readlane_b32 s3, v254, 12
	s_waitcnt vmcnt(0)
	v_add_u32_e32 v16, v16, v5
	s_nop 2
	global_load_dword v6, v213, s[2:3] sc1
	v_readlane_b32 s2, v254, 13
	v_readlane_b32 s3, v254, 14
	s_waitcnt vmcnt(0)
	v_add_u32_e32 v16, v16, v6
	s_nop 2
	global_load_dword v7, v213, s[2:3] sc1
	v_readlane_b32 s2, v254, 15
	v_readlane_b32 s3, v254, 16
	s_waitcnt vmcnt(0)
	v_add_u32_e32 v16, v16, v7
	s_nop 2
	global_load_dword v8, v213, s[2:3] sc1
	v_readlane_b32 s2, v254, 17
	v_readlane_b32 s3, v254, 18
	s_waitcnt vmcnt(0)
	v_add_u32_e32 v16, v16, v8
	s_nop 2
	global_load_dword v9, v213, s[2:3] sc1
	v_readlane_b32 s2, v254, 19
	v_readlane_b32 s3, v254, 20
	s_waitcnt vmcnt(0)
	v_add_u32_e32 v16, v16, v9
	s_nop 2
	global_load_dword v10, v213, s[2:3] sc1
	v_readlane_b32 s2, v254, 21
	v_readlane_b32 s3, v254, 22
	s_waitcnt vmcnt(0)
	v_add_u32_e32 v16, v16, v10
	s_nop 2
	global_load_dword v11, v213, s[2:3] sc1
	v_readlane_b32 s2, v254, 23
	v_readlane_b32 s3, v254, 24
	s_waitcnt vmcnt(0)
	v_add_u32_e32 v16, v16, v11
	s_nop 2
	global_load_dword v12, v213, s[2:3] sc1
	v_readlane_b32 s2, v254, 25
	v_readlane_b32 s3, v254, 26
	s_waitcnt vmcnt(0)
	v_add_u32_e32 v16, v16, v12
	s_nop 2
	global_load_dword v13, v213, s[2:3] sc1
	v_readlane_b32 s2, v254, 27
	v_readlane_b32 s3, v254, 28
	s_waitcnt vmcnt(0)
	v_add_u32_e32 v16, v16, v13
	s_nop 2
	global_load_dword v14, v213, s[2:3] sc1
	v_readlane_b32 s2, v254, 29
	v_readlane_b32 s3, v254, 30
	s_waitcnt vmcnt(0)
	v_add_u32_e32 v16, v16, v14
	s_nop 2
	global_load_dword v15, v213, s[2:3] sc1
	s_mov_b64 s[2:3], -1
	s_waitcnt vmcnt(0)
	v_add_u32_e32 v16, v16, v15
	v_cmp_eq_u32_e32 vcc, s83, v16
	s_cbranch_vccnz .LBB0_270
	s_and_b32 s2, s5, 0xff
	s_cmp_eq_u32 s2, 0
	s_mov_b64 s[2:3], -1
	s_mov_b64 s[12:13], -1
	s_sleep 3
	s_cbranch_scc1 .LBB0_275
	s_and_b64 vcc, exec, s[12:13]
	s_cbranch_vccz .LBB0_270

.LBB0_289:
	s_and_b32 s5, s4, 0xff
	s_mov_b64 s[18:19], -1
	s_cmp_lg_u32 s5, 0
	s_mov_b64 s[34:35], -1
	s_sleep 3
	s_cbranch_scc0 .LBB0_292
	s_and_b64 vcc, exec, s[34:35]
	s_cbranch_vccz .LBB0_288

.LBB0_306:
	s_and_b32 s8, s5, 0xff
	s_mov_b64 s[18:19], -1
	s_cmp_lg_u32 s8, 0
	s_mov_b64 s[34:35], -1
	s_sleep 3
	s_cbranch_scc0 .LBB0_309
	s_and_b64 vcc, exec, s[34:35]
	s_cbranch_vccz .LBB0_305

; __device__ __forceinline__ unsigned xb_ld(unsigned* p)              { return __hip_atomic_load(p, __ATOMIC_RELAXED, __HIP_MEMORY_SCOPE_AGENT); }
; __device__ __forceinline__ unsigned xb_add(unsigned* p, unsigned v) { return __hip_atomic_fetch_add(p, v, __ATOMIC_RELAXED, __HIP_MEMORY_SCOPE_AGENT); }
; #define XB_SPIN(cond, bar) do { unsigned _sp = 0; while (cond) { __builtin_amdgcn_s_sleep(1); \
;     if ((++_sp & 255u) == 0u) { if (xb_ld(&(bar)[XB_TMO])) break; if (_sp > XB_SPIN_CAP) { atomicAdd(&(bar)[XB_TMO], 1u); break; } } } } while (0)
; __device__ __forceinline__ void xcd_barrier(const XcdBarrier& b, int tid) {
;     ...
;             else XB_SPIN(xb_ld(&bar[XB_TOPGEN]) == tg, bar);
;             __builtin_amdgcn_fence(__ATOMIC_ACQUIRE, "agent");
;             xb_add(&bar[XB_XGEN(b.x)], 1u);
;             asm volatile("s_waitcnt vmcnt(0)" ::: "memory");
;         } else {
;             XB_SPIN(xb_ld(&bar[XB_XGEN(b.x)]) == gen, bar);
.LBB0_2175:
	s_sleep 3
	global_load_dword v2, v0, s[2:3] offset:32 sc1
	s_waitcnt vmcnt(0)
	v_and_b32_e32 v2, 0xffff0000, v2
	v_cmp_ne_u32_e32 vcc, v2, v1
	s_or_b64 s[6:7], vcc, s[6:7]
	s_andn2_b64 exec, exec, s[6:7]
	s_cbranch_execnz .LBB0_2175

; __device__ __forceinline__ unsigned xb_ld(unsigned* p)              { return __hip_atomic_load(p, __ATOMIC_RELAXED, __HIP_MEMORY_SCOPE_AGENT); }
; __device__ __forceinline__ void xcd_barrier_complete(unsigned* bar, unsigned x, unsigned& nloc, unsigned& nx) {
;     const unsigned G = gridDim.x * gridDim.y * gridDim.z;
;     unsigned sum, cnt, mine, sp = 0u;
;     for (;;) {
;         sum = 0u; cnt = 0u; mine = 0u;
; #pragma unroll
;         for (unsigned j = 0; j < 16; ++j) { const unsigned c = xb_ld(&bar[XB_XCNT(j)]); sum += c; cnt += (c > 0u) ? 1u : 0u; mine = (j == x) ? c : mine; }
;         if (sum == G) break;
;         __builtin_amdgcn_s_sleep(1);
;         if ((++sp & 255u) == 0u) { if (xb_ld(&bar[XB_TMO])) break; if (sp > XB_SPIN_CAP) { atomicAdd(&bar[XB_TMO], 1u); break; } }
;     }
;     nloc = mine > 0u ? mine : 1u; nx = cnt > 0u ? cnt : 1u;
; }
.LBB0_2182:
	v_readlane_b32 s2, v254, 5
	v_readlane_b32 s3, v254, 6
	global_load_dword v2, v16, s[90:91] sc1
	s_waitcnt lgkmcnt(0)
	global_load_dword v0, v16, s[92:93] sc1
	global_load_dword v1, v16, s[86:87] sc1
	s_mov_b64 s[6:7], -1
	s_waitcnt vmcnt(1)
	v_add_u32_e32 v17, v0, v2
	global_load_dword v3, v16, s[2:3] sc1
	v_readlane_b32 s2, v254, 7
	v_readlane_b32 s3, v254, 8
	s_waitcnt vmcnt(1)
	v_add_u32_e32 v17, v17, v1
	s_waitcnt vmcnt(0)
	v_add_u32_e32 v17, v17, v3
	s_nop 0
	global_load_dword v4, v16, s[2:3] sc1
	v_readlane_b32 s2, v254, 9
	v_readlane_b32 s3, v254, 10
	s_waitcnt vmcnt(0)
	v_add_u32_e32 v17, v17, v4
	s_nop 2
	global_load_dword v5, v16, s[2:3] sc1
	v_readlane_b32 s2, v254, 11
	v_readlane_b32 s3, v254, 12
	s_waitcnt vmcnt(0)
	v_add_u32_e32 v17, v17, v5
	s_nop 2
	global_load_dword v6, v16, s[2:3] sc1
	v_readlane_b32 s2, v254, 13
	v_readlane_b32 s3, v254, 14
	s_waitcnt vmcnt(0)
	v_add_u32_e32 v17, v17, v6
	s_nop 2
	global_load_dword v7, v16, s[2:3] sc1
	v_readlane_b32 s2, v254, 15
	v_readlane_b32 s3, v254, 16
	s_waitcnt vmcnt(0)
	v_add_u32_e32 v17, v17, v7
	s_nop 2
	global_load_dword v8, v16, s[2:3] sc1
	v_readlane_b32 s2, v254, 17
	v_readlane_b32 s3, v254, 18
	s_waitcnt vmcnt(0)
	v_add_u32_e32 v17, v17, v8
	s_nop 2
	global_load_dword v9, v16, s[2:3] sc1
	v_readlane_b32 s2, v254, 19
	v_readlane_b32 s3, v254, 20
	s_waitcnt vmcnt(0)
	v_add_u32_e32 v17, v17, v9
	s_nop 2
	global_load_dword v10, v16, s[2:3] sc1
	v_readlane_b32 s2, v254, 21
	v_readlane_b32 s3, v254, 22
	s_waitcnt vmcnt(0)
	v_add_u32_e32 v17, v17, v10
	s_nop 2
	global_load_dword v11, v16, s[2:3] sc1
	v_readlane_b32 s2, v254, 23
	v_readlane_b32 s3, v254, 24
	s_waitcnt vmcnt(0)
	v_add_u32_e32 v17, v17, v11
	s_nop 2
	global_load_dword v12, v16, s[2:3] sc1
	v_readlane_b32 s2, v254, 25
	v_readlane_b32 s3, v254, 26
	s_waitcnt vmcnt(0)
	v_add_u32_e32 v17, v17, v12
	s_nop 2
	global_load_dword v13, v16, s[2:3] sc1
	v_readlane_b32 s2, v254, 27
	v_readlane_b32 s3, v254, 28
	s_waitcnt vmcnt(0)
	v_add_u32_e32 v17, v17, v13
	s_nop 2
	global_load_dword v14, v16, s[2:3] sc1
	v_readlane_b32 s2, v254, 29
	v_readlane_b32 s3, v254, 30
	s_waitcnt vmcnt(0)
	v_add_u32_e32 v17, v17, v14
	s_nop 2
	global_load_dword v15, v16, s[2:3] sc1
	s_mov_b64 s[2:3], -1
	s_waitcnt vmcnt(0)
	v_add_u32_e32 v17, v17, v15
	v_cmp_eq_u32_e32 vcc, s83, v17
	s_cbranch_vccnz .LBB0_2181
	s_and_b32 s2, s4, 0xff
	s_cmp_eq_u32 s2, 0
	s_mov_b64 s[2:3], -1
	s_mov_b64 s[8:9], -1
	s_sleep 3
	s_cbranch_scc1 .LBB0_2186
	s_and_b64 vcc, exec, s[8:9]
	s_cbranch_vccz .LBB0_2181

.LBB0_2200:
	s_and_b32 s12, s16, 0xff
	s_mov_b64 s[10:11], -1
	s_cmp_lg_u32 s12, 0
	s_mov_b64 s[14:15], -1
	s_sleep 3
	s_cbranch_scc0 .LBB0_2203
	s_and_b64 vcc, exec, s[14:15]
	s_cbranch_vccz .LBB0_2199

.LBB0_2217:
	s_and_b32 s10, s16, 0xff
	s_cmp_lg_u32 s10, 0
	s_mov_b64 s[12:13], -1
	s_sleep 3
	s_cbranch_scc0 .LBB0_2220
	s_mov_b64 s[14:15], -1
	s_and_b64 vcc, exec, s[12:13]
	s_cbranch_vccz .LBB0_2216
